# v7 plus the p to bf16 copy (layer l) and the w_in transpose of layer l+1 also moved into the scan phase loader waves
# speedup vs baseline: 1.0044x; 1.0044x over previous
.LBB0_86:
	s_mul_i32 s1, s22, 0x1200000
	s_mov_b32 s23, s17
	s_mul_hi_u32 s0, s22, 0x1200000
	s_add_u32 s34, s14, s1
	s_addc_u32 s35, s15, s0
	s_lshl_b64 s[0:1], s[22:23], 13
	s_add_u32 s50, s6, s0
	s_addc_u32 s51, s7, s1
	v_lshlrev_b32_e32 v36, 2, v14
	v_lshlrev_b32_e32 v156, 2, v16
	v_lshlrev_b32_e32 v38, 1, v14
	v_lshlrev_b32_e32 v57, 5, v10
	s_and_saveexec_b64 s[24:25], s[38:39]
	s_cbranch_execz .LBB0_92
	s_cmp_lg_u32 s22, 0
	s_cbranch_scc1 .LBB0_92
	s_load_dwordx2 s[0:1], s[28:29], 0x18
	s_mul_i32 s16, s22, 0x2240000
	s_mul_hi_u32 s9, s22, 0x2240000
	v_mov_b32_e32 v37, v157
	v_mov_b32_e32 v39, v157
	s_waitcnt lgkmcnt(0)
	s_add_u32 s0, s0, s16
	s_addc_u32 s1, s1, s9
	v_lshl_add_u64 v[40:41], s[50:51], 0, v[36:37]
	v_lshl_add_u64 v[42:43], s[0:1], 0, v[156:157]
	v_lshl_add_u64 v[44:45], s[34:35], 0, v[38:39]
	v_lshlrev_b32_e32 v46, 5, v10
	s_lshl_b32 s0, s8, 5
	s_mov_b64 s[30:31], 0
	v_mov_b32_e32 v35, v10
	s_branch .LBB0_90

.LBB0_161:
	s_or_b64 exec, exec, s[6:7]
	s_mov_b64 s[0:1], 0x200000
	v_cmp_gt_u64_e32 vcc, s[0:1], v[8:9]
	s_and_saveexec_b64 s[6:7], vcc
	s_branch .LBB0_164
	s_load_dwordx2 s[0:1], s[28:29], 0x8
	v_lshl_add_u64 v[0:1], s[4:5], 0, v[12:13]
	s_lshl_b64 s[4:5], s[12:13], 14
	v_lshlrev_b64 v[2:3], 5, v[160:161]
	s_mov_b64 s[14:15], 0x19b00000
	s_waitcnt lgkmcnt(0)
	s_add_u32 s0, s0, s4
	s_addc_u32 s1, s1, s5
	v_lshl_add_u64 v[2:3], s[0:1], 0, v[2:3]
	v_lshl_add_u64 v[0:1], v[0:1], 0, s[14:15]
	v_lshl_add_u64 v[2:3], v[2:3], 0, 16
	s_mov_b64 s[4:5], 0

.LBB0_190:
	v_readfirstlane_b32 s13, v160
	s_ashr_i32 s13, s13, 6
	s_cmp_gt_i32 s13, 3
	s_mov_b64 s[14:15], -1
	s_cbranch_scc0 .LBB0_219
	s_load_dwordx2 s[50:51], s[28:29], 0xa8
	s_load_dwordx2 s[52:53], s[28:29], 0xd0
	s_load_dwordx2 s[58:59], s[28:29], 0xc0
	s_load_dwordx2 s[60:61], s[28:29], 0xb8
	s_load_dwordx2 s[62:63], s[28:29], 0xc8
	s_load_dwordx2 s[64:65], s[28:29], 0xb0
	s_load_dwordx2 s[66:67], s[28:29], 0xf0
	v_readlane_b32 s56, v254, 22
	v_lshrrev_b32_e32 v222, 3, v197
	v_and_b32_e32 v223, 7, v197
	v_lshlrev_b32_e32 v217, 2, v222
	v_mul_u32_u24_e32 v218, 33, v222
	v_lshl_add_u32 v218, v223, 2, v218
	v_lshlrev_b32_e32 v218, 2, v218
	v_and_b32_e32 v223, 3, v197
	v_lshrrev_b32_e32 v222, 2, v197
	v_mul_u32_u24_e32 v219, 0x108, v223
	v_add_lshl_u32 v219, v219, v222, 2
	s_sub_u32 s57, s13, 4
	s_mul_i32 s55, s57, 0x1080
	s_add_u32 s55, s55, 0x16000
	v_add_u32_e32 v218, s55, v218
	v_add_u32_e32 v219, s55, v219
	v_readlane_b32 s55, v253, 0
	s_lshl_b32 s55, s55, 2
	s_add_u32 s55, s55, s57
	s_waitcnt lgkmcnt(0)
	s_lshl_b32 s57, s56, 24
	s_add_u32 s50, s50, s57
	s_addc_u32 s51, s51, 0
	v_writelane_b32 v224, s50, 0
	v_writelane_b32 v224, s51, 1
	s_lshl_b32 s57, s56, 24
	s_add_u32 s52, s52, s57
	s_addc_u32 s53, s53, 0
	v_writelane_b32 v224, s52, 2
	v_writelane_b32 v224, s53, 3
	s_lshl_b32 s57, s56, 26
	s_add_u32 s58, s58, s57
	s_addc_u32 s59, s59, 0
	v_writelane_b32 v224, s58, 4
	v_writelane_b32 v224, s59, 5
	s_lshl_b32 s57, s56, 26
	s_add_u32 s60, s60, s57
	s_addc_u32 s61, s61, 0
	v_writelane_b32 v224, s60, 6
	v_writelane_b32 v224, s61, 7
	s_lshl_b32 s57, s56, 13
	s_add_u32 s62, s62, s57
	s_addc_u32 s63, s63, 0
	v_writelane_b32 v224, s62, 8
	v_writelane_b32 v224, s63, 9
	s_lshl_b32 s57, s56, 13
	s_add_u32 s64, s64, s57
	s_addc_u32 s65, s65, 0
	v_writelane_b32 v224, s64, 10
	v_writelane_b32 v224, s65, 11
	s_lshl_b32 s57, s56, 23
	s_add_u32 s50, s66, s57
	s_addc_u32 s51, s67, 0
	s_add_u32 s50, s50, 0x4900000
	s_addc_u32 s51, s51, 0
	v_writelane_b32 v224, s50, 12
	v_writelane_b32 v224, s51, 13
	s_lshl_b32 s57, s56, 23
	s_add_u32 s50, s66, s57
	s_addc_u32 s51, s67, 0
	s_add_u32 s50, s50, 0x16900000
	s_addc_u32 s51, s51, 0
	v_writelane_b32 v224, s50, 14
	v_writelane_b32 v224, s51, 15
	s_lshl_b32 s57, s56, 25
	s_add_u32 s50, s66, s57
	s_addc_u32 s51, s67, 0
	s_add_u32 s50, s50, 0xe900000
	s_addc_u32 s51, s51, 0
	v_writelane_b32 v224, s50, 16
	v_writelane_b32 v224, s51, 17
	s_lshl_b32 s57, s56, 25
	s_add_u32 s50, s66, s57
	s_addc_u32 s51, s67, 0
	s_add_u32 s50, s50, 0x6900000
	s_addc_u32 s51, s51, 0
	v_writelane_b32 v224, s50, 18
	v_writelane_b32 v224, s51, 19
	s_load_dwordx2 s[50:51], s[28:29], 0x8
	s_load_dwordx2 s[52:53], s[28:29], 0x18
	s_load_dwordx2 s[58:59], s[28:29], 0x10
	s_waitcnt lgkmcnt(0)
	s_lshl_b32 s57, s56, 24
	s_add_u32 s50, s50, s57
	s_addc_u32 s51, s51, 0
	v_writelane_b32 v224, s50, 20
	v_writelane_b32 v224, s51, 21
	s_lshl_b32 s57, s56, 23
	s_add_u32 s60, s66, s57
	s_addc_u32 s61, s67, 0
	s_add_u32 s60, s60, 0x19b00000
	s_addc_u32 s61, s61, 0
	v_writelane_b32 v224, s60, 22
	v_writelane_b32 v224, s61, 23
	s_add_u32 s57, s56, 1
	s_mul_i32 s60, s57, 0x2240000
	s_mul_hi_u32 s61, s57, 0x2240000
	s_add_u32 s52, s52, s60
	s_addc_u32 s53, s53, s61
	v_writelane_b32 v224, s52, 24
	v_writelane_b32 v224, s53, 25
	s_lshl_b32 s60, s57, 13
	s_add_u32 s58, s58, s60
	s_addc_u32 s59, s59, 0
	v_writelane_b32 v224, s58, 26
	v_writelane_b32 v224, s59, 27
	s_mul_i32 s60, s57, 0x1200000
	s_mul_hi_u32 s61, s57, 0x1200000
	s_add_u32 s60, s60, s66
	s_addc_u32 s61, s61, s67
	s_add_u32 s60, s60, 0x100000
	s_addc_u32 s61, s61, 0
	v_writelane_b32 v224, s60, 28
	v_writelane_b32 v224, s61, 29
	s_mov_b32 s60, 0xb000
	s_cmp_lt_u32 s56, 3
	s_cselect_b32 s60, 0xd240, s60
	v_writelane_b32 v224, s60, 30
	s_mov_b32 s53, 0
	s_load_dwordx2 s[14:15], s[28:29], 0xf0
	s_ashr_i32 s20, s0, 6
	s_ashr_i32 s21, s20, 31
	s_lshl_b32 s16, s0, 4
	s_lshl_b64 s[22:23], s[20:21], 12
	s_and_b32 s16, s16, 0x3c0
	s_waitcnt lgkmcnt(0)
	s_add_u32 s30, s14, 0x28700000
	s_addc_u32 s31, s15, 0
	s_load_dwordx2 s[18:19], s[28:29], 0x20
	s_load_dwordx4 s[44:47], s[28:29], 0x80
	s_add_u32 s34, s14, 0x31700000
	s_addc_u32 s35, s15, 0
	s_add_u32 s24, s14, 0x26700000
	v_readlane_b32 s26, v254, 22
	s_addc_u32 s25, s15, 0
	s_mov_b32 s48, s26
	s_mulk_i32 s26, 0x3480
	v_or_b32_e32 v46, s16, v161
	s_waitcnt lgkmcnt(0)
	s_add_u32 s18, s18, s26
	s_mul_hi_u32 s26, s48, 0x3480
	s_addc_u32 s19, s19, s26
	v_lshlrev_b32_e32 v156, 2, v46
	v_lshl_add_u64 v[0:1], s[18:19], 0, v[156:157]
	global_load_dwordx4 v[28:31], v156, s[18:19] offset:16
	global_load_dwordx4 v[8:11], v156, s[18:19]
	s_mov_b64 s[18:19], 0x1000
	v_lshl_add_u64 v[2:3], v[0:1], 0, s[18:19]
	v_add_co_u32_e32 v4, vcc, s69, v0
	s_mov_b64 s[18:19], 0x2000
	s_nop 0
	v_addc_co_u32_e32 v5, vcc, 0, v1, vcc
	v_lshl_add_u64 v[0:1], v[0:1], 0, s[18:19]
	s_add_u32 s18, s44, s6
	s_addc_u32 s19, s45, s7
	global_load_dwordx4 v[24:27], v[4:5], off offset:-4096
	global_load_dwordx4 v[32:35], v[4:5], off
	global_load_dwordx4 v[20:23], v[2:3], off offset:16
	global_load_dwordx4 v[36:39], v[0:1], off offset:16
	global_load_dwordx4 v[16:19], v156, s[18:19] offset:16
	global_load_dwordx4 v[12:15], v156, s[18:19]
	s_add_u32 s18, s46, s6
	s_addc_u32 s19, s47, s7
	v_lshl_add_u64 v[48:49], s[22:23], 0, v[120:121]
	v_mov_b64_e32 v[42:43], s[30:31]
	global_load_dwordx4 v[0:3], v156, s[18:19] offset:16
	global_load_dwordx4 v[4:7], v156, s[18:19]
	v_mad_u64_u32 v[44:45], s[18:19], v48, s75, v[42:43]
	v_lshl_add_u64 v[40:41], v[48:49], 0, v[122:123]
	v_mad_i32_i24 v45, v49, s75, v45
	v_lshlrev_b32_e32 v156, 1, v46
	v_lshl_add_u64 v[44:45], v[44:45], 0, v[156:157]
	v_mad_u64_u32 v[42:43], s[18:19], v40, s75, v[42:43]
	v_mad_i32_i24 v43, v41, s75, v43
	v_add_co_u32_e32 v40, vcc, s74, v44
	v_lshl_add_u64 v[46:47], v[42:43], 0, v[156:157]
	s_nop 0
	v_addc_co_u32_e32 v41, vcc, 0, v45, vcc
	global_load_dwordx4 v[88:91], v[40:41], off
	s_nop 0
	global_load_dwordx4 v[40:43], v[40:41], off offset:2048
	s_nop 0
	global_load_dwordx4 v[92:95], v[44:45], off offset:2048
	global_load_dwordx4 v[68:71], v[46:47], off offset:2048
	v_add_co_u32_e32 v44, vcc, s74, v46
	v_lshlrev_b64 v[144:145], 11, v[48:49]
	s_nop 0
	v_addc_co_u32_e32 v45, vcc, 0, v47, vcc
	global_load_dwordx4 v[64:67], v[44:45], off
	global_load_dwordx4 v[56:59], v[44:45], off offset:2048
	v_lshl_add_u64 v[44:45], s[34:35], 0, v[144:145]
	s_add_u32 s46, s14, 0x33700000
	v_lshl_add_u64 v[44:45], v[44:45], 0, v[156:157]
	s_addc_u32 s47, s15, 0
	global_load_dwordx4 v[60:63], v[44:45], off
	v_lshl_add_u64 v[44:45], s[46:47], 0, v[144:145]
	v_lshl_add_u64 v[44:45], v[44:45], 0, v[156:157]
	global_load_dwordx4 v[44:47], v[44:45], off
	v_cndmask_b32_e64 v50, 0, 1, s[2:3]
	v_cmp_ne_u32_e64 s[44:45], 1, v50
	s_andn2_b64 vcc, exec, s[2:3]
	v_readlane_b32 s27, v254, 23
	s_waitcnt vmcnt(1)
	v_mov_b64_e32 v[102:103], v[62:63]
	v_mov_b64_e32 v[106:107], v[62:63]
	v_mov_b64_e32 v[100:101], v[60:61]
	v_mov_b64_e32 v[104:105], v[60:61]
	s_cbranch_vccnz .LBB0_193
	v_lshlrev_b64 v[48:49], 10, v[48:49]
	v_lshlrev_b64 v[48:49], 1, v[48:49]
	v_lshl_add_u64 v[50:51], s[14:15], 0, v[48:49]
	v_lshl_add_u64 v[50:51], v[50:51], 0, v[156:157]
	v_add_co_u32_e32 v50, vcc, 0x37700000, v50
	v_lshl_add_u64 v[48:49], s[24:25], 0, v[48:49]
	s_nop 0
	v_addc_co_u32_e32 v51, vcc, 0, v51, vcc
	v_lshl_add_u64 v[48:49], v[48:49], 0, v[156:157]
	global_load_dwordx4 v[100:103], v[50:51], off
	global_load_dwordx4 v[104:107], v[48:49], off

.LBB0_208:
	s_mov_b32 s53, 0
	v_readlane_b32 s52, v224, 30
	s_nop 3
	s_cmp_lt_u32 s55, s52
	s_cbranch_scc0 .Lcis_a_done
	s_mov_b32 s53, 1
	s_cmp_lt_u32 s55, 0x1000
	s_cbranch_scc1 .Lcis_j_wout
	s_cmp_lt_u32 s55, 0x2000
	s_cbranch_scc1 .Lcis_j_gate
	s_cmp_lt_u32 s55, 0x6000
	s_cbranch_scc1 .Lcis_j_down
	s_cmp_lt_u32 s55, 0xa000
	s_cbranch_scc1 .Lcis_j_up
	s_cmp_lt_u32 s55, 0xb000
	s_cbranch_scc1 .Lcis_j_p
.Lcis_j_win:
	s_sub_u32 s51, s55, 0xb000
	s_mul_hi_u32 s50, s51, 0x1de5d6f
	s_mul_i32 s52, s50, 137
	s_sub_u32 s51, s51, s52
	s_mov_b32 s57, 0x4480
	s_movk_i32 s61, 1
	s_movk_i32 s66, 12
	s_mov_b32 s67, 0x10000
	v_readlane_b32 s58, v224, 24
	v_readlane_b32 s59, v224, 25
	v_readlane_b32 s64, v224, 28
	v_readlane_b32 s65, v224, 29
	v_readlane_b32 s62, v224, 26
	v_readlane_b32 s63, v224, 27
	s_branch .Lcis_j_common
.Lcis_j_up:
	s_sub_u32 s51, s55, 0x6000
	s_lshr_b32 s50, s51, 8
	s_and_b32 s51, s51, 0xff
	s_mov_b32 s57, 0x8000
	s_movk_i32 s61, 1
	s_movk_i32 s66, 12
	s_mov_b32 s67, 0x10000
	v_readlane_b32 s58, v224, 6
	v_readlane_b32 s59, v224, 7
	v_readlane_b32 s64, v224, 18
	v_readlane_b32 s65, v224, 19
	v_readlane_b32 s62, v224, 10
	v_readlane_b32 s63, v224, 11
	s_branch .Lcis_j_common
.Lcis_j_down:
	s_sub_u32 s51, s55, 0x2000
	s_lshr_b32 s50, s51, 6
	s_and_b32 s51, s51, 0x3f
	s_mov_b32 s57, 0x2000
	s_movk_i32 s61, 0
	s_movk_i32 s66, 14
	s_mov_b32 s67, 0x40000
	v_readlane_b32 s58, v224, 4
	v_readlane_b32 s59, v224, 5
	v_readlane_b32 s64, v224, 16
	v_readlane_b32 s65, v224, 17
	s_branch .Lcis_j_common
.Lcis_j_gate:
	s_sub_u32 s51, s55, 0x1000
	s_lshr_b32 s50, s51, 6
	s_and_b32 s51, s51, 0x3f
	s_mov_b32 s57, 0x2000
	s_movk_i32 s61, 1
	s_movk_i32 s66, 12
	s_mov_b32 s67, 0x10000
	v_readlane_b32 s58, v224, 2
	v_readlane_b32 s59, v224, 3
	v_readlane_b32 s64, v224, 14
	v_readlane_b32 s65, v224, 15
	v_readlane_b32 s62, v224, 8
	v_readlane_b32 s63, v224, 9
	s_branch .Lcis_j_common
.Lcis_j_wout:
	s_sub_u32 s51, s55, 0x0
	s_lshr_b32 s50, s51, 6
	s_and_b32 s51, s51, 0x3f
	s_mov_b32 s57, 0x2000
	s_movk_i32 s61, 0
	s_movk_i32 s66, 12
	s_mov_b32 s67, 0x10000
	v_readlane_b32 s58, v224, 0
	v_readlane_b32 s59, v224, 1
	v_readlane_b32 s64, v224, 12
	v_readlane_b32 s65, v224, 13
.Lcis_j_common:
	s_lshl_b32 s60, s57, 3
	s_lshl_b32 s52, s57, 5
	s_mul_i32 s52, s52, s50
	s_add_u32 s58, s58, s52
	s_addc_u32 s59, s59, 0
	s_lshl_b32 s52, s51, 7
	s_add_u32 s58, s58, s52
	s_addc_u32 s59, s59, 0
	s_add_u32 s52, s66, 5
	s_lshl_b32 s52, s51, s52
	s_add_u32 s64, s64, s52
	s_addc_u32 s65, s65, 0
	s_lshl_b32 s52, s50, 6
	s_add_u32 s64, s64, s52
	s_addc_u32 s65, s65, 0
	v_lshrrev_b32_e32 v222, 3, v197
	v_and_b32_e32 v223, 7, v197
	v_mul_u32_u24_e32 v216, s57, v222
	v_lshl_add_u32 v216, v223, 4, v216
	global_load_dwordx4 v[232:235], v216, s[58:59]
	s_add_u32 s58, s58, s60
	s_addc_u32 s59, s59, 0
	global_load_dwordx4 v[236:239], v216, s[58:59]
	s_add_u32 s58, s58, s60
	s_addc_u32 s59, s59, 0
	global_load_dwordx4 v[240:243], v216, s[58:59]
	s_add_u32 s58, s58, s60
	s_addc_u32 s59, s59, 0
	global_load_dwordx4 v[244:247], v216, s[58:59]
	s_cmp_eq_u32 s61, 0
	s_cbranch_scc1 .Lcis_a_done
	s_lshl_b32 s52, s50, 7
	s_add_u32 s62, s62, s52
	s_addc_u32 s63, s63, 0
	global_load_dword v248, v217, s[62:63] offset:0
	global_load_dword v249, v217, s[62:63] offset:32
	global_load_dword v250, v217, s[62:63] offset:64
	global_load_dword v251, v217, s[62:63] offset:96
	s_branch .Lcis_a_done
.Lcis_j_p:
	s_sub_u32 s51, s55, 0xa000
	s_movk_i32 s61, 2
	v_readlane_b32 s58, v224, 20
	v_readlane_b32 s59, v224, 21
	v_readlane_b32 s64, v224, 22
	v_readlane_b32 s65, v224, 23
	s_lshl_b32 s52, s51, 12
	s_add_u32 s58, s58, s52
	s_addc_u32 s59, s59, 0
	s_lshl_b32 s52, s51, 11
	s_add_u32 s64, s64, s52
	s_addc_u32 s65, s65, 0
	v_lshlrev_b32_e32 v216, 5, v197
	global_load_dwordx4 v[232:235], v216, s[58:59]
	global_load_dwordx4 v[236:239], v216, s[58:59] offset:16
	global_load_dwordx4 v[240:243], v216, s[58:59] offset:2048
	global_load_dwordx4 v[244:247], v216, s[58:59] offset:2064

.LBB0_212:
	s_or_b64 exec, exec, s[22:23]
	s_and_b32 s22, s24, 0x800
	s_addk_i32 s24, 0x800
	v_add_u32_e32 v40, s22, v171
	s_add_u32 s20, s20, 32
	ds_read_b64 v[40:41], v40
	s_addc_u32 s21, s21, 0
	s_mov_b64 s[22:23], 0x48000
	s_add_i32 s19, s19, 1
	s_waitcnt lgkmcnt(0)
	v_cvt_pk_bf16_f32 v42, v40, v41
	v_lshl_add_u64 v[40:41], s[14:15], 0, v[148:149]
	v_lshl_add_u64 v[148:149], v[148:149], 0, s[92:93]
	v_lshl_add_u64 v[150:151], v[150:151], 0, s[92:93]
	v_lshl_add_u64 v[154:155], v[154:155], 0, s[22:23]
	s_cmp_eq_u32 s53, 1
	s_cbranch_scc0 .Lcis_b_done
	s_waitcnt vmcnt(0)
	s_cmp_eq_u32 s61, 2
	s_cbranch_scc1 .Lcis_b_flat
	s_cmp_eq_u32 s61, 0
	s_cbranch_scc1 .Lcis_b_nogs
	v_mul_f32_e32 v232, v232, v248
	v_mul_f32_e32 v233, v233, v248
	v_mul_f32_e32 v234, v234, v248
	v_mul_f32_e32 v235, v235, v248
	v_mul_f32_e32 v236, v236, v249
	v_mul_f32_e32 v237, v237, v249
	v_mul_f32_e32 v238, v238, v249
	v_mul_f32_e32 v239, v239, v249
	v_mul_f32_e32 v240, v240, v250
	v_mul_f32_e32 v241, v241, v250
	v_mul_f32_e32 v242, v242, v250
	v_mul_f32_e32 v243, v243, v250
	v_mul_f32_e32 v244, v244, v251
	v_mul_f32_e32 v245, v245, v251
	v_mul_f32_e32 v246, v246, v251
	v_mul_f32_e32 v247, v247, v251
.Lcis_b_nogs:
	ds_write_b32 v218, v232 offset:0
	ds_write_b32 v218, v233 offset:4
	ds_write_b32 v218, v234 offset:8
	ds_write_b32 v218, v235 offset:12
	ds_write_b32 v218, v236 offset:1056
	ds_write_b32 v218, v237 offset:1060
	ds_write_b32 v218, v238 offset:1064
	ds_write_b32 v218, v239 offset:1068
	ds_write_b32 v218, v240 offset:2112
	ds_write_b32 v218, v241 offset:2116
	ds_write_b32 v218, v242 offset:2120
	ds_write_b32 v218, v243 offset:2124
	ds_write_b32 v218, v244 offset:3168
	ds_write_b32 v218, v245 offset:3172
	ds_write_b32 v218, v246 offset:3176
	ds_write_b32 v218, v247 offset:3180
	v_lshrrev_b32_e32 v222, 2, v197
	v_and_b32_e32 v223, 3, v197
	v_lshlrev_b32_e32 v220, s66, v222
	v_lshl_add_u32 v220, v223, 4, v220
	s_waitcnt lgkmcnt(0)
	ds_read2_b32 v[208:209], v219 offset0:0 offset1:33
	ds_read2_b32 v[210:211], v219 offset0:66 offset1:99
	ds_read2_b32 v[212:213], v219 offset0:132 offset1:165
	ds_read2_b32 v[214:215], v219 offset0:198 offset1:231
	s_waitcnt lgkmcnt(0)
	v_cvt_pk_bf16_f32 v208, v208, v209
	v_cvt_pk_bf16_f32 v209, v210, v211
	v_cvt_pk_bf16_f32 v210, v212, v213
	v_cvt_pk_bf16_f32 v211, v214, v215
	global_store_dwordx4 v220, v[208:211], s[64:65]
	s_add_u32 s64, s64, s67
	s_addc_u32 s65, s65, 0
	ds_read2_b32 v[208:209], v219 offset0:16 offset1:49
	ds_read2_b32 v[210:211], v219 offset0:82 offset1:115
	ds_read2_b32 v[212:213], v219 offset0:148 offset1:181
	ds_read2_b32 v[214:215], v219 offset0:214 offset1:247
	s_waitcnt lgkmcnt(0)
	v_cvt_pk_bf16_f32 v208, v208, v209
	v_cvt_pk_bf16_f32 v209, v210, v211
	v_cvt_pk_bf16_f32 v210, v212, v213
	v_cvt_pk_bf16_f32 v211, v214, v215
	global_store_dwordx4 v220, v[208:211], s[64:65]
	s_branch .Lcis_b_next
.Lcis_b_flat:
	v_cvt_pk_bf16_f32 v208, v232, v233
	v_cvt_pk_bf16_f32 v209, v234, v235
	v_cvt_pk_bf16_f32 v210, v236, v237
	v_cvt_pk_bf16_f32 v211, v238, v239
	v_cvt_pk_bf16_f32 v212, v240, v241
	v_cvt_pk_bf16_f32 v213, v242, v243
	v_cvt_pk_bf16_f32 v214, v244, v245
	v_cvt_pk_bf16_f32 v215, v246, v247
	v_lshlrev_b32_e32 v220, 4, v197
	global_store_dwordx4 v220, v[208:211], s[64:65]
	global_store_dwordx4 v220, v[212:215], s[64:65] offset:1024
.Lcis_b_next:
	s_lshl_b32 s50, s80, 2
	s_add_u32 s55, s55, s50
